# GEMM-1 activation LDS-DMA ring deepened to 4 buffers (prefetch distance 3 K-steps)
# baseline (speedup 1.0000x reference)
.LBB0_161:
	v_and_b32_e32 v246, 63, v208
	v_lshrrev_b32_e32 v247, 6, v208
	v_lshrrev_b32_e32 v248, 3, v246
	v_and_b32_e32 v249, 7, v246
	v_xor_b32_e32 v249, v249, v248
	v_lshlrev_b32_e32 v249, 4, v249
	v_lshl_add_u32 v250, v247, 5, v248
	v_lshl_add_u32 v234, v250, 11, v249
	v_add_u32_e32 v235, 0x4000, v234
	v_add_u32_e32 v236, 0x8000, v234
	v_add_u32_e32 v237, 0xc000, v234
	v_lshlrev_b32_e32 v238, 4, v246
	v_add_u32_e32 v239, 0x8000, v238
	v_add_u32_e32 v240, 0x10000, v238
	v_add_u32_e32 v241, 0x18000, v238
	v_readfirstlane_b32 s0, v247
	s_lshl_b32 s97, s0, 12
	v_and_b32_e32 v251, 15, v246
	v_lshrrev_b32_e32 v252, 4, v246
	v_and_b32_e32 v253, 7, v251
	v_xor_b32_e32 v253, v253, v252
	v_lshlrev_b32_e32 v253, 4, v253
	v_lshl_add_u32 v242, v251, 7, v253
	v_xor_b32_e32 v243, 64, v242
	v_lshlrev_b32_e32 v244, 2, v251
	s_lshl_b32 s0, s24, 9
	s_add_i32 s0, s0, 0x36b00000
	v_add_u32_e32 v244, s0, v244
	v_mov_b32_e32 v245, s93
	v_add_co_u32_e32 v244, vcc, s92, v244
	s_nop 1
	v_addc_co_u32_e32 v245, vcc, 0, v245, vcc
	global_load_dword v246, v[244:245], off
	global_load_dword v247, v[244:245], off offset:64
	global_load_dword v248, v[244:245], off offset:128
	global_load_dword v249, v[244:245], off offset:192
	global_load_dword v250, v[244:245], off offset:256
	global_load_dword v251, v[244:245], off offset:320
	global_load_dword v252, v[244:245], off offset:384
	global_load_dword v253, v[244:245], off offset:448
	v_mov_b32_e32 v0, 0
	v_mov_b32_e32 v1, 0
	v_mov_b32_e32 v2, 0
	v_mov_b32_e32 v3, 0
	v_mov_b32_e32 v4, 0
	v_mov_b32_e32 v5, 0
	v_mov_b32_e32 v6, 0
	v_mov_b32_e32 v7, 0
	v_mov_b32_e32 v8, 0
	v_mov_b32_e32 v9, 0
	v_mov_b32_e32 v10, 0
	v_mov_b32_e32 v11, 0
	v_mov_b32_e32 v12, 0
	v_mov_b32_e32 v13, 0
	v_mov_b32_e32 v14, 0
	v_mov_b32_e32 v15, 0
	v_mov_b32_e32 v16, 0
	v_mov_b32_e32 v17, 0
	v_mov_b32_e32 v18, 0
	v_mov_b32_e32 v19, 0
	v_mov_b32_e32 v20, 0
	v_mov_b32_e32 v21, 0
	v_mov_b32_e32 v22, 0
	v_mov_b32_e32 v23, 0
	v_mov_b32_e32 v24, 0
	v_mov_b32_e32 v25, 0
	v_mov_b32_e32 v26, 0
	v_mov_b32_e32 v27, 0
	v_mov_b32_e32 v28, 0
	v_mov_b32_e32 v29, 0
	v_mov_b32_e32 v30, 0
	v_mov_b32_e32 v31, 0
	v_mov_b32_e32 v32, 0
	v_mov_b32_e32 v33, 0
	v_mov_b32_e32 v34, 0
	v_mov_b32_e32 v35, 0
	v_mov_b32_e32 v36, 0
	v_mov_b32_e32 v37, 0
	v_mov_b32_e32 v38, 0
	v_mov_b32_e32 v39, 0
	v_mov_b32_e32 v40, 0
	v_mov_b32_e32 v41, 0
	v_mov_b32_e32 v42, 0
	v_mov_b32_e32 v43, 0
	v_mov_b32_e32 v44, 0
	v_mov_b32_e32 v45, 0
	v_mov_b32_e32 v46, 0
	v_mov_b32_e32 v47, 0
	v_mov_b32_e32 v48, 0
	v_mov_b32_e32 v49, 0
	v_mov_b32_e32 v50, 0
	v_mov_b32_e32 v51, 0
	v_mov_b32_e32 v52, 0
	v_mov_b32_e32 v53, 0
	v_mov_b32_e32 v54, 0
	v_mov_b32_e32 v55, 0
	v_mov_b32_e32 v56, 0
	v_mov_b32_e32 v57, 0
	v_mov_b32_e32 v58, 0
	v_mov_b32_e32 v59, 0
	v_mov_b32_e32 v60, 0
	v_mov_b32_e32 v61, 0
	v_mov_b32_e32 v62, 0
	v_mov_b32_e32 v63, 0
	v_mov_b32_e32 v64, 0
	v_mov_b32_e32 v65, 0
	v_mov_b32_e32 v66, 0
	v_mov_b32_e32 v67, 0
	v_mov_b32_e32 v68, 0
	v_mov_b32_e32 v69, 0
	v_mov_b32_e32 v70, 0
	v_mov_b32_e32 v71, 0
	v_mov_b32_e32 v72, 0
	v_mov_b32_e32 v73, 0
	v_mov_b32_e32 v74, 0
	v_mov_b32_e32 v75, 0
	v_mov_b32_e32 v76, 0
	v_mov_b32_e32 v77, 0
	v_mov_b32_e32 v78, 0
	v_mov_b32_e32 v79, 0
	v_mov_b32_e32 v80, 0
	v_mov_b32_e32 v81, 0
	v_mov_b32_e32 v82, 0
	v_mov_b32_e32 v83, 0
	v_mov_b32_e32 v84, 0
	v_mov_b32_e32 v85, 0
	v_mov_b32_e32 v86, 0
	v_mov_b32_e32 v87, 0
	v_mov_b32_e32 v88, 0
	v_mov_b32_e32 v89, 0
	v_mov_b32_e32 v90, 0
	v_mov_b32_e32 v91, 0
	v_mov_b32_e32 v92, 0
	v_mov_b32_e32 v93, 0
	v_mov_b32_e32 v94, 0
	v_mov_b32_e32 v95, 0
	v_mov_b32_e32 v96, 0
	v_mov_b32_e32 v97, 0
	v_mov_b32_e32 v98, 0
	v_mov_b32_e32 v99, 0
	v_mov_b32_e32 v100, 0
	v_mov_b32_e32 v101, 0
	v_mov_b32_e32 v102, 0
	v_mov_b32_e32 v103, 0
	v_mov_b32_e32 v104, 0
	v_mov_b32_e32 v105, 0
	v_mov_b32_e32 v106, 0
	v_mov_b32_e32 v107, 0
	v_mov_b32_e32 v108, 0
	v_mov_b32_e32 v109, 0
	v_mov_b32_e32 v110, 0
	v_mov_b32_e32 v111, 0
	v_mov_b32_e32 v112, 0
	v_mov_b32_e32 v113, 0
	v_mov_b32_e32 v114, 0
	v_mov_b32_e32 v115, 0
	v_mov_b32_e32 v116, 0
	v_mov_b32_e32 v117, 0
	v_mov_b32_e32 v118, 0
	v_mov_b32_e32 v119, 0
	v_mov_b32_e32 v120, 0
	v_mov_b32_e32 v121, 0
	v_mov_b32_e32 v122, 0
	v_mov_b32_e32 v123, 0
	v_mov_b32_e32 v124, 0
	v_mov_b32_e32 v125, 0
	v_mov_b32_e32 v126, 0
	v_mov_b32_e32 v127, 0
	s_lshr_b32 s0, s32, 16
	s_and_b32 s28, s32, 0xffff
	s_add_i32 s27, s28, 0xc000
	s_and_b32 s27, s27, 0xffff
	s_cmp_eq_u32 s0, 0x600d
	s_cbranch_scc1 .Lg1_pre
	s_lshl_b32 s0, s24, 18
	s_add_u32 s58, s92, s0
	s_addc_u32 s59, s93, 0
	s_lshl_b32 s0, s97, 5
	s_lshl_b32 s25, s26, 19
	s_add_i32 s0, s0, s25
	s_add_u32 s56, s92, s0
	s_addc_u32 s57, s93, 0
	s_add_u32 s56, s56, 0x34000000
	s_addc_u32 s57, s57, 0
	s_mov_b32 s25, 0
	s_mov_b32 s27, 0
	s_add_i32 m0, s27, s97
	s_nop 0
	global_load_lds_dwordx4 v234, s[58:59]
	s_add_i32 m0, m0, 0x400
	s_nop 0
	global_load_lds_dwordx4 v235, s[58:59]
	s_add_i32 m0, m0, 0x400
	s_nop 0
	global_load_lds_dwordx4 v236, s[58:59]
	s_add_i32 m0, m0, 0x400
	s_nop 0
	global_load_lds_dwordx4 v237, s[58:59]
	s_add_u32 s58, s58, 128
	s_addc_u32 s59, s59, 0
	global_load_dwordx4 v[128:131], v238, s[56:57]
	global_load_dwordx4 v[132:135], v239, s[56:57]
	global_load_dwordx4 v[136:139], v240, s[56:57]
	global_load_dwordx4 v[140:143], v241, s[56:57]
	s_add_u32 s56, s56, 1024
	s_addc_u32 s57, s57, 0
	s_add_i32 s25, s25, 1
	s_movk_i32 s27, 0x4000
	s_add_i32 m0, s27, s97
	s_nop 0
	global_load_lds_dwordx4 v234, s[58:59]
	s_add_i32 m0, m0, 0x400
	s_nop 0
	global_load_lds_dwordx4 v235, s[58:59]
	s_add_i32 m0, m0, 0x400
	s_nop 0
	global_load_lds_dwordx4 v236, s[58:59]
	s_add_i32 m0, m0, 0x400
	s_nop 0
	global_load_lds_dwordx4 v237, s[58:59]
	s_add_u32 s58, s58, 128
	s_addc_u32 s59, s59, 0
	global_load_dwordx4 v[144:147], v238, s[56:57]
	global_load_dwordx4 v[148:151], v239, s[56:57]
	global_load_dwordx4 v[152:155], v240, s[56:57]
	global_load_dwordx4 v[156:159], v241, s[56:57]
	s_add_u32 s56, s56, 1024
	s_addc_u32 s57, s57, 0
	s_add_i32 s25, s25, 1
	s_mov_b32 s27, 0x8000
	s_add_i32 m0, s27, s97
	s_nop 0
	global_load_lds_dwordx4 v234, s[58:59]
	s_add_i32 m0, m0, 0x400
	s_nop 0
	global_load_lds_dwordx4 v235, s[58:59]
	s_add_i32 m0, m0, 0x400
	s_nop 0
	global_load_lds_dwordx4 v236, s[58:59]
	s_add_i32 m0, m0, 0x400
	s_nop 0
	global_load_lds_dwordx4 v237, s[58:59]
	s_add_u32 s58, s58, 128
	s_addc_u32 s59, s59, 0
	global_load_dwordx4 v[160:163], v238, s[56:57]
	global_load_dwordx4 v[164:167], v239, s[56:57]
	global_load_dwordx4 v[168:171], v240, s[56:57]
	global_load_dwordx4 v[172:175], v241, s[56:57]
	s_add_u32 s56, s56, 1024
	s_addc_u32 s57, s57, 0
	s_add_i32 s25, s25, 1
	s_mov_b32 s28, 0
	s_mov_b32 s27, 0xc000

.Lg1_ndw0:
.Lg1_swdw0:
	s_add_i32 s25, s25, 1
	s_add_i32 m0, s27, s97
	s_nop 0
	global_load_lds_dwordx4 v234, s[58:59]
	s_add_i32 m0, m0, 0x400
	s_nop 0
	global_load_lds_dwordx4 v235, s[58:59]
	s_add_i32 m0, m0, 0x400
	s_nop 0
	global_load_lds_dwordx4 v236, s[58:59]
	s_add_i32 m0, m0, 0x400
	s_nop 0
	global_load_lds_dwordx4 v237, s[58:59]
	s_cmp_eq_u32 s29, 12
	s_cbranch_scc1 .Lg1_saa1
	s_add_u32 s58, s58, 128
	s_addc_u32 s59, s59, 0
	s_branch .Lg1_sada1

.Lg1_ndw2:
.Lg1_swdw2:
	s_add_i32 s25, s25, 1
	ds_read_b128 v[198:201], v245 offset:0
	ds_read_b128 v[202:205], v245 offset:2048
	ds_read_b128 v[210:213], v245 offset:4096
	ds_read_b128 v[214:217], v245 offset:6144
	ds_read_b128 v[218:221], v245 offset:8192
	ds_read_b128 v[222:225], v245 offset:10240
	ds_read_b128 v[226:229], v245 offset:12288
	ds_read_b128 v[230:233], v245 offset:14336
	s_waitcnt lgkmcnt(4)
	v_mfma_f32_16x16x32_bf16 v[0:3], v[144:147], v[198:201], v[0:3]
	v_mfma_f32_16x16x32_bf16 v[32:35], v[148:151], v[198:201], v[32:35]
	v_mfma_f32_16x16x32_bf16 v[64:67], v[152:155], v[198:201], v[64:67]
	v_mfma_f32_16x16x32_bf16 v[96:99], v[156:159], v[198:201], v[96:99]
	v_mfma_f32_16x16x32_bf16 v[4:7], v[144:147], v[202:205], v[4:7]
	v_mfma_f32_16x16x32_bf16 v[36:39], v[148:151], v[202:205], v[36:39]
	v_mfma_f32_16x16x32_bf16 v[68:71], v[152:155], v[202:205], v[68:71]
	v_mfma_f32_16x16x32_bf16 v[100:103], v[156:159], v[202:205], v[100:103]
	v_mfma_f32_16x16x32_bf16 v[8:11], v[144:147], v[210:213], v[8:11]
	v_mfma_f32_16x16x32_bf16 v[40:43], v[148:151], v[210:213], v[40:43]
	v_mfma_f32_16x16x32_bf16 v[72:75], v[152:155], v[210:213], v[72:75]
	v_mfma_f32_16x16x32_bf16 v[104:107], v[156:159], v[210:213], v[104:107]
	v_mfma_f32_16x16x32_bf16 v[12:15], v[144:147], v[214:217], v[12:15]
	v_mfma_f32_16x16x32_bf16 v[44:47], v[148:151], v[214:217], v[44:47]
	v_mfma_f32_16x16x32_bf16 v[76:79], v[152:155], v[214:217], v[76:79]
	v_mfma_f32_16x16x32_bf16 v[108:111], v[156:159], v[214:217], v[108:111]
	s_waitcnt lgkmcnt(0)
	v_mfma_f32_16x16x32_bf16 v[16:19], v[144:147], v[218:221], v[16:19]
	v_mfma_f32_16x16x32_bf16 v[48:51], v[148:151], v[218:221], v[48:51]
	v_mfma_f32_16x16x32_bf16 v[80:83], v[152:155], v[218:221], v[80:83]
	v_mfma_f32_16x16x32_bf16 v[112:115], v[156:159], v[218:221], v[112:115]
	v_mfma_f32_16x16x32_bf16 v[20:23], v[144:147], v[222:225], v[20:23]
	v_mfma_f32_16x16x32_bf16 v[52:55], v[148:151], v[222:225], v[52:55]
	v_mfma_f32_16x16x32_bf16 v[84:87], v[152:155], v[222:225], v[84:87]
	v_mfma_f32_16x16x32_bf16 v[116:119], v[156:159], v[222:225], v[116:119]
	v_mfma_f32_16x16x32_bf16 v[24:27], v[144:147], v[226:229], v[24:27]
	v_mfma_f32_16x16x32_bf16 v[56:59], v[148:151], v[226:229], v[56:59]
	v_mfma_f32_16x16x32_bf16 v[88:91], v[152:155], v[226:229], v[88:91]
	v_mfma_f32_16x16x32_bf16 v[120:123], v[156:159], v[226:229], v[120:123]
	v_mfma_f32_16x16x32_bf16 v[28:31], v[144:147], v[230:233], v[28:31]
	v_mfma_f32_16x16x32_bf16 v[60:63], v[148:151], v[230:233], v[60:63]
	v_mfma_f32_16x16x32_bf16 v[92:95], v[152:155], v[230:233], v[92:95]
	v_mfma_f32_16x16x32_bf16 v[124:127], v[156:159], v[230:233], v[124:127]
	s_add_i32 s28, s28, 0x4000
	s_and_b32 s28, s28, 0xffff
	s_add_i32 s27, s27, 0x4000
	s_and_b32 s27, s27, 0xffff
	s_add_i32 s29, s29, 1
	s_waitcnt vmcnt(12)
	s_barrier
	global_load_dwordx4 v[144:147], v238, s[56:57]
	global_load_dwordx4 v[148:151], v239, s[56:57]
	global_load_dwordx4 v[152:155], v240, s[56:57]
	global_load_dwordx4 v[156:159], v241, s[56:57]
	s_cmp_eq_u32 s25, 31
	s_cbranch_scc1 .Lg1_sww3
	s_add_u32 s56, s56, 1024
	s_addc_u32 s57, s57, 0
	s_branch .Lg1_swdw3

.Lg1_ndw5:
.Lg1_swdw5:
	s_add_i32 s25, s25, 1
	ds_read_b128 v[198:201], v245 offset:0
	ds_read_b128 v[202:205], v245 offset:2048
	ds_read_b128 v[210:213], v245 offset:4096
	ds_read_b128 v[214:217], v245 offset:6144
	ds_read_b128 v[218:221], v245 offset:8192
	ds_read_b128 v[222:225], v245 offset:10240
	ds_read_b128 v[226:229], v245 offset:12288
	ds_read_b128 v[230:233], v245 offset:14336
	s_waitcnt lgkmcnt(4)
	v_mfma_f32_16x16x32_bf16 v[0:3], v[176:179], v[198:201], v[0:3]
	v_mfma_f32_16x16x32_bf16 v[32:35], v[182:185], v[198:201], v[32:35]
	v_mfma_f32_16x16x32_bf16 v[64:67], v[186:189], v[198:201], v[64:67]
	v_mfma_f32_16x16x32_bf16 v[96:99], v[194:197], v[198:201], v[96:99]
	v_mfma_f32_16x16x32_bf16 v[4:7], v[176:179], v[202:205], v[4:7]
	v_mfma_f32_16x16x32_bf16 v[36:39], v[182:185], v[202:205], v[36:39]
	v_mfma_f32_16x16x32_bf16 v[68:71], v[186:189], v[202:205], v[68:71]
	v_mfma_f32_16x16x32_bf16 v[100:103], v[194:197], v[202:205], v[100:103]
	v_mfma_f32_16x16x32_bf16 v[8:11], v[176:179], v[210:213], v[8:11]
	v_mfma_f32_16x16x32_bf16 v[40:43], v[182:185], v[210:213], v[40:43]
	v_mfma_f32_16x16x32_bf16 v[72:75], v[186:189], v[210:213], v[72:75]
	v_mfma_f32_16x16x32_bf16 v[104:107], v[194:197], v[210:213], v[104:107]
	v_mfma_f32_16x16x32_bf16 v[12:15], v[176:179], v[214:217], v[12:15]
	v_mfma_f32_16x16x32_bf16 v[44:47], v[182:185], v[214:217], v[44:47]
	v_mfma_f32_16x16x32_bf16 v[76:79], v[186:189], v[214:217], v[76:79]
	v_mfma_f32_16x16x32_bf16 v[108:111], v[194:197], v[214:217], v[108:111]
	s_waitcnt lgkmcnt(0)
	v_mfma_f32_16x16x32_bf16 v[16:19], v[176:179], v[218:221], v[16:19]
	v_mfma_f32_16x16x32_bf16 v[48:51], v[182:185], v[218:221], v[48:51]
	v_mfma_f32_16x16x32_bf16 v[80:83], v[186:189], v[218:221], v[80:83]
	v_mfma_f32_16x16x32_bf16 v[112:115], v[194:197], v[218:221], v[112:115]
	v_mfma_f32_16x16x32_bf16 v[20:23], v[176:179], v[222:225], v[20:23]
	v_mfma_f32_16x16x32_bf16 v[52:55], v[182:185], v[222:225], v[52:55]
	v_mfma_f32_16x16x32_bf16 v[84:87], v[186:189], v[222:225], v[84:87]
	v_mfma_f32_16x16x32_bf16 v[116:119], v[194:197], v[222:225], v[116:119]
	v_mfma_f32_16x16x32_bf16 v[24:27], v[176:179], v[226:229], v[24:27]
	v_mfma_f32_16x16x32_bf16 v[56:59], v[182:185], v[226:229], v[56:59]
	v_mfma_f32_16x16x32_bf16 v[88:91], v[186:189], v[226:229], v[88:91]
	v_mfma_f32_16x16x32_bf16 v[120:123], v[194:197], v[226:229], v[120:123]
	v_mfma_f32_16x16x32_bf16 v[28:31], v[176:179], v[230:233], v[28:31]
	v_mfma_f32_16x16x32_bf16 v[60:63], v[182:185], v[230:233], v[60:63]
	v_mfma_f32_16x16x32_bf16 v[92:95], v[186:189], v[230:233], v[92:95]
	v_mfma_f32_16x16x32_bf16 v[124:127], v[194:197], v[230:233], v[124:127]
	s_add_i32 s28, s28, 0x4000
	s_and_b32 s28, s28, 0xffff
	s_add_i32 s27, s27, 0x4000
	s_and_b32 s27, s27, 0xffff
	s_add_i32 s29, s29, 1
	s_cmp_lt_u32 s29, 16
	s_cbranch_scc1 .Lg1_loop
	s_mov_b32 s32, 0
	s_add_i32 s0, s30, s36
	s_cmp_lt_i32 s0, s31
	s_cbranch_scc0 .Lg1_nf
	s_cmp_eq_u64 s[2:3], 0
	s_cbranch_scc0 .Lg1_nf
	s_mov_b32 s32, 0x600d0000
	s_or_b32 s32, s32, s28
